# v109 plus sliding-window QK section with its K-fragment LDS reads issued ahead of the MFMAs (ring of read buffers, counted waits)
# baseline (speedup 1.0000x reference)
; __device__ void swa_item(const Params& p, int item) {
;     ...
;   { long qrow = rowb + (long)(qb * 128 + w * 16 + c) * dil + r;
;     _Pragma("unroll") for (int kk = 0; kk < 4; ++kk) qf[kk] = *(const bf16x8*)(buf + qrow * 4608 + qcol + kk * 32 + q * 8); }
;   __syncthreads();
;   f32x4 S[9];
;   _Pragma("unroll") for (int ci = 0; ci < 9; ++ci) {
;     const int ct = w + ci;
;     f32x4 a = (f32x4){0.f, 0.f, 0.f, 0.f};
;     _Pragma("unroll") for (int kk = 0; kk < 4; ++kk) {
;       bf16x8 kf = *(const bf16x8*)(Ks + (ct * 16 + c) * 136 + kk * 32 + q * 8);
;       a = __builtin_amdgcn_mfma_f32_16x16x32_bf16(qf[kk], kf, a, 0, 0, 0);
;     }
;     S[ci] = a;
;   }
.LBB0_111:
	s_or_b64 exec, exec, s[12:13]
	s_movk_i32 s2, 0x1500
	v_lshlrev_b32_e32 v58, 4, v12
	v_mul_lo_u32 v2, v12, s2
	v_readlane_b32 s12, v254, 10
	v_add_u32_e32 v51, s35, v58
	v_readlane_b32 s26, v254, 13
	v_add_u32_e32 v57, s12, v2
	v_or_b32_e32 v2, v51, v55
	v_ashrrev_i32_e32 v3, 31, v2
	v_lshlrev_b64 v[2:3], s22, v[2:3]
	v_readlane_b32 s27, v254, 14
	v_mov_b64_e32 v[4:5], s[16:17]
	v_and_b32_e32 v52, 48, v50
	v_lshl_add_u64 v[2:3], v[2:3], 0, s[26:27]
	v_mad_u64_u32 v[4:5], s[2:3], v2, s89, v[4:5]
	v_mad_i32_i24 v5, v3, s89, v5
	v_lshl_add_u64 v[2:3], s[0:1], 1, v[4:5]
	v_mov_b32_e32 v53, v1
	v_lshl_add_u64 v[2:3], v[2:3], 0, v[52:53]
	global_load_dwordx4 v[46:49], v[2:3], off
	global_load_dwordx4 v[42:45], v[2:3], off offset:64
	global_load_dwordx4 v[38:41], v[2:3], off offset:128
	global_load_dwordx4 v[34:37], v[2:3], off offset:192
	v_add_u32_e32 v54, s12, v52
	v_or_b32_e32 v53, v58, v55
	s_movk_i32 s3, 0x110
	v_mad_u64_u32 v[30:31], s[0:1], v53, s3, v[54:55]
	s_waitcnt lgkmcnt(0)
	s_barrier
	v_bfe_u32 v56, v50, 4, 2
	s_cmp_lg_u32 s34, 0
	s_movk_i32 s2, 0x7f
	v_add_u32_e32 v62, 32, v53
	s_cselect_b64 s[14:15], -1, 0
	s_movk_i32 s18, 0x81
	v_add_u32_e32 v63, 48, v53
	v_add_u32_e32 v61, 16, v53
	v_add_u32_e32 v64, 64, v53
	v_add_u32_e32 v65, 0x50, v53
	v_add_u32_e32 v74, 0x60, v53
	v_add_u32_e32 v75, 0x70, v53
	v_and_b32_e32 v60, 63, v50
	v_add_u32_e32 v72, 0x80, v58
	v_or_b32_e32 v59, v72, v55
	v_mad_u64_u32 v[70:71], s[0:1], v59, s3, v[54:55]
	v_cmp_lt_i32_e64 s[0:1], s2, v53
	s_or_b64 s[12:13], s[14:15], s[0:1]
	v_cmp_lt_i32_e64 s[0:1], s2, v62
	s_or_b64 s[38:39], s[14:15], s[0:1]
	v_cmp_lt_i32_e64 s[0:1], s2, v63
	v_mov_b32_e32 v66, 0xf149f2ca
	s_or_b64 s[40:41], s[14:15], s[0:1]
	v_cmp_lt_i32_e64 s[0:1], s2, v64
	s_or_b64 s[42:43], s[14:15], s[0:1]
	v_mov_b32_e32 v144, v30
	ds_read_b128 v[76:79], v144 offset:0
	ds_read_b128 v[80:83], v144 offset:64
	ds_read_b128 v[84:87], v144 offset:128
	ds_read_b128 v[88:91], v144 offset:192
	ds_read_b128 v[92:95], v144 offset:4352
	ds_read_b128 v[96:99], v144 offset:4416
	ds_read_b128 v[100:103], v144 offset:4480
	ds_read_b128 v[104:107], v144 offset:4544
	ds_read_b128 v[108:111], v144 offset:8704
	ds_read_b128 v[112:115], v144 offset:8768
	ds_read_b128 v[116:119], v144 offset:8832
	ds_read_b128 v[120:123], v144 offset:8896
	ds_read_b128 v[124:127], v144 offset:13056
	ds_read_b128 v[128:131], v144 offset:13120
	ds_read_b128 v[132:135], v144 offset:13184
	s_waitcnt vmcnt(0)
	s_waitcnt lgkmcnt(14)
	v_mfma_f32_16x16x32_bf16 v[2:5], v[46:49], v[76:79], 0
	ds_read_b128 v[136:139], v144 offset:13248
	s_waitcnt lgkmcnt(14)
	v_mfma_f32_16x16x32_bf16 v[2:5], v[42:45], v[80:83], v[2:5]
	ds_read_b128 v[76:79], v144 offset:17408
	s_waitcnt lgkmcnt(14)
	v_mfma_f32_16x16x32_bf16 v[2:5], v[38:41], v[84:87], v[2:5]
	ds_read_b128 v[80:83], v144 offset:17472
	s_waitcnt lgkmcnt(14)
	v_mfma_f32_16x16x32_bf16 v[2:5], v[34:37], v[88:91], v[2:5]
	ds_read_b128 v[84:87], v144 offset:17536
	s_waitcnt lgkmcnt(14)
	v_mfma_f32_16x16x32_bf16 v[6:9], v[46:49], v[92:95], 0
	ds_read_b128 v[88:91], v144 offset:17600
	s_waitcnt lgkmcnt(14)
	v_mfma_f32_16x16x32_bf16 v[6:9], v[42:45], v[96:99], v[6:9]
	ds_read_b128 v[92:95], v144 offset:21760
	s_waitcnt lgkmcnt(14)
	v_mfma_f32_16x16x32_bf16 v[6:9], v[38:41], v[100:103], v[6:9]
	ds_read_b128 v[96:99], v144 offset:21824
	s_waitcnt lgkmcnt(14)
	v_mfma_f32_16x16x32_bf16 v[6:9], v[34:37], v[104:107], v[6:9]
	ds_read_b128 v[100:103], v144 offset:21888
	s_waitcnt lgkmcnt(14)
	v_mfma_f32_16x16x32_bf16 v[10:13], v[46:49], v[108:111], 0
	ds_read_b128 v[104:107], v144 offset:21952
	s_waitcnt lgkmcnt(14)
	v_mfma_f32_16x16x32_bf16 v[10:13], v[42:45], v[112:115], v[10:13]
	ds_read_b128 v[108:111], v144 offset:26112
	s_waitcnt lgkmcnt(14)
	v_mfma_f32_16x16x32_bf16 v[10:13], v[38:41], v[116:119], v[10:13]
	ds_read_b128 v[112:115], v144 offset:26176
	s_waitcnt lgkmcnt(14)
	v_mfma_f32_16x16x32_bf16 v[10:13], v[34:37], v[120:123], v[10:13]
	ds_read_b128 v[116:119], v144 offset:26240
	s_waitcnt lgkmcnt(14)
	v_mfma_f32_16x16x32_bf16 v[14:17], v[46:49], v[124:127], 0
	ds_read_b128 v[120:123], v144 offset:26304
	s_waitcnt lgkmcnt(14)
	v_mfma_f32_16x16x32_bf16 v[14:17], v[42:45], v[128:131], v[14:17]
	ds_read_b128 v[124:127], v144 offset:30464
	s_waitcnt lgkmcnt(14)
	v_mfma_f32_16x16x32_bf16 v[14:17], v[38:41], v[132:135], v[14:17]
	ds_read_b128 v[128:131], v144 offset:30528
	s_waitcnt lgkmcnt(14)
	v_mfma_f32_16x16x32_bf16 v[14:17], v[34:37], v[136:139], v[14:17]
	ds_read_b128 v[132:135], v144 offset:30592
	s_waitcnt lgkmcnt(14)
	v_mfma_f32_16x16x32_bf16 v[18:21], v[46:49], v[76:79], 0
	ds_read_b128 v[136:139], v144 offset:30656
	s_waitcnt lgkmcnt(14)
	v_mfma_f32_16x16x32_bf16 v[18:21], v[42:45], v[80:83], v[18:21]
	ds_read_b128 v[76:79], v144 offset:34816
	s_waitcnt lgkmcnt(14)
	v_mfma_f32_16x16x32_bf16 v[18:21], v[38:41], v[84:87], v[18:21]
	ds_read_b128 v[80:83], v144 offset:34880
	s_waitcnt lgkmcnt(14)
	v_mfma_f32_16x16x32_bf16 v[18:21], v[34:37], v[88:91], v[18:21]
	ds_read_b128 v[84:87], v144 offset:34944
	s_waitcnt lgkmcnt(14)
	v_mfma_f32_16x16x32_bf16 v[22:25], v[46:49], v[92:95], 0
	ds_read_b128 v[88:91], v144 offset:35008
	s_waitcnt lgkmcnt(14)
	v_mfma_f32_16x16x32_bf16 v[22:25], v[42:45], v[96:99], v[22:25]
	s_waitcnt lgkmcnt(13)
	v_mfma_f32_16x16x32_bf16 v[22:25], v[38:41], v[100:103], v[22:25]
	s_waitcnt lgkmcnt(12)
	v_mfma_f32_16x16x32_bf16 v[22:25], v[34:37], v[104:107], v[22:25]
	s_waitcnt lgkmcnt(11)
	v_mfma_f32_16x16x32_bf16 v[26:29], v[46:49], v[108:111], 0
	s_waitcnt lgkmcnt(10)
	v_mfma_f32_16x16x32_bf16 v[26:29], v[42:45], v[112:115], v[26:29]
	s_waitcnt lgkmcnt(9)
; #define SHX(v, m) shx_((v), (m), lane)
; __device__ void swa_item(const Params& p, int item) {
;     ...
;   _Pragma("unroll") for (int ci = 0; ci < 9; ++ci) {
;     const int ct = w + ci;
;     f32x4 a = (f32x4){0.f, 0.f, 0.f, 0.f};
;     _Pragma("unroll") for (int kk = 0; kk < 4; ++kk) {
;       bf16x8 kf = *(const bf16x8*)(Ks + (ct * 16 + c) * 136 + kk * 32 + q * 8);
;       a = __builtin_amdgcn_mfma_f32_16x16x32_bf16(qf[kk], kf, a, 0, 0, 0);
;     }
;     S[ci] = a;
;   }
;   float mx[4], ls[4];
;   _Pragma("unroll") for (int jj = 0; jj < 4; ++jj) {
;     const int qi = w * 16 + q * 4 + jj;
;     float m = -1e30f;
;     _Pragma("unroll") for (int ci = 0; ci < 9; ++ci) {
;       int kj = (w + ci) * 16 + c; int dist = qi + 128 - kj;
;       bool valid = (dist >= 0) && (dist <= 128) && (qb > 0 || kj >= 128);
;       float s = valid ? S[ci][jj] : -1e30f;
;       S[ci][jj] = s; m = fmaxf(m, s);
;     }
;     m = fmaxf(m, SHX(m, 1)); m = fmaxf(m, SHX(m, 2)); m = fmaxf(m, SHX(m, 4)); m = fmaxf(m, SHX(m, 8));
	v_mfma_f32_16x16x32_bf16 v[26:29], v[38:41], v[116:119], v[26:29]
	s_waitcnt lgkmcnt(8)
	v_mfma_f32_16x16x32_bf16 v[26:29], v[34:37], v[120:123], v[26:29]
	s_waitcnt lgkmcnt(7)
	v_mfma_f32_16x16x32_bf16 v[30:33], v[46:49], v[124:127], 0
	s_waitcnt lgkmcnt(6)
	v_mfma_f32_16x16x32_bf16 v[30:33], v[42:45], v[128:131], v[30:33]
	s_waitcnt lgkmcnt(5)
	v_mfma_f32_16x16x32_bf16 v[30:33], v[38:41], v[132:135], v[30:33]
	s_waitcnt lgkmcnt(4)
	v_mfma_f32_16x16x32_bf16 v[30:33], v[34:37], v[136:139], v[30:33]
	s_waitcnt lgkmcnt(3)
	v_mfma_f32_16x16x32_bf16 v[140:143], v[46:49], v[76:79], 0
	s_waitcnt lgkmcnt(2)
	v_mfma_f32_16x16x32_bf16 v[140:143], v[42:45], v[80:83], v[140:143]
	s_waitcnt lgkmcnt(1)
	v_mfma_f32_16x16x32_bf16 v[140:143], v[38:41], v[84:87], v[140:143]
	s_waitcnt lgkmcnt(0)
	v_mfma_f32_16x16x32_bf16 v[34:37], v[34:37], v[88:91], v[140:143]
	v_cmp_lt_i32_e64 s[0:1], s2, v65
	s_nop 1
	v_lshlrev_b32_e32 v38, 2, v56
	v_or_b32_e32 v43, v72, v38
	v_sub_u32_e32 v44, v43, v53
	v_cmp_gt_u32_e32 vcc, s18, v44
	s_and_b64 vcc, vcc, s[12:13]
	v_cndmask_b32_e64 v45, v66, v10, s[38:39]
	v_cndmask_b32_e32 v2, v66, v2, vcc
	v_cmp_lt_i32_e32 vcc, s2, v61
	v_max_f32_e32 v44, v2, v2
	s_or_b64 vcc, s[14:15], vcc
	v_max_f32_e32 v44, 0xf149f2ca, v44
	v_cndmask_b32_e32 v6, v66, v6, vcc
	s_or_b64 s[44:45], s[14:15], s[0:1]
	v_cmp_lt_i32_e64 s[0:1], s2, v74
	v_max3_f32 v10, v44, v6, v45
	v_cndmask_b32_e64 v44, v66, v18, s[42:43]
	s_or_b64 s[46:47], s[14:15], s[0:1]
	v_cmp_lt_i32_e64 s[0:1], s2, v75
	v_sub_u32_e32 v18, v38, v55
	v_cmp_lt_i32_e64 s[50:51], s2, v59
	v_cndmask_b32_e64 v14, v66, v14, s[40:41]
	s_or_b64 s[48:49], s[14:15], s[0:1]
	v_cmp_gt_u32_e64 s[0:1], s18, v18
	s_or_b64 s[14:15], s[14:15], s[50:51]
	v_max3_f32 v10, v10, v14, v44
	v_cndmask_b32_e64 v46, v66, v22, s[44:45]
	v_cndmask_b32_e64 v26, v66, v26, s[46:47]
	s_and_b64 s[0:1], s[0:1], s[14:15]
	v_lshlrev_b32_e32 v39, 2, v60
	v_max3_f32 v10, v10, v46, v26
	v_cndmask_b32_e64 v47, v66, v30, s[48:49]
	v_cndmask_b32_e64 v48, v66, v34, s[0:1]
	v_xor_b32_e32 v42, 4, v39
	v_max3_f32 v10, v10, v47, v48
	v_xor_b32_e32 v41, 8, v39
	v_xor_b32_e32 v40, 16, v39
	v_xor_b32_e32 v39, 32, v39
	s_mov_b32 s2, 0xefa18f08
	s_waitcnt lgkmcnt(0)
	s_nop 1
	v_max_f32_dpp v10, v10, v10 row_ror:1 row_mask:0xf bank_mask:0xf
	v_cmp_lt_f32_e64 s[0:1], s2, v2
	v_cndmask_b32_e32 v7, v66, v7, vcc
	v_cndmask_b32_e64 v15, v66, v15, s[40:41]
	v_cndmask_b32_e64 v49, v66, v23, s[44:45]
	s_waitcnt lgkmcnt(0)
	s_nop 1
	v_max_f32_dpp v10, v10, v10 row_ror:2 row_mask:0xf bank_mask:0xf
	v_cndmask_b32_e64 v27, v66, v27, s[46:47]
	v_cndmask_b32_e64 v54, v66, v31, s[48:49]
	v_cndmask_b32_e32 v8, v66, v8, vcc
	v_cndmask_b32_e64 v12, v66, v12, s[38:39]
	s_waitcnt lgkmcnt(0)
	s_nop 1
	v_max_f32_dpp v10, v10, v10 row_ror:4 row_mask:0xf bank_mask:0xf
	v_cndmask_b32_e64 v60, v66, v32, s[48:49]
	v_cndmask_b32_e64 v16, v66, v16, s[40:41]
	v_cndmask_b32_e64 v20, v66, v20, s[42:43]
	v_cndmask_b32_e64 v28, v66, v28, s[46:47]
	s_waitcnt lgkmcnt(0)
	s_nop 1
	v_max_f32_dpp v22, v10, v10 row_ror:8 row_mask:0xf bank_mask:0xf
	v_sub_f32_e32 v2, v2, v22
	v_mul_f32_e32 v2, 0x3fb8aa3b, v2
	v_exp_f32_e32 v2, v2
	v_sub_f32_e32 v34, v46, v22
	v_mul_f32_e32 v34, 0x3fb8aa3b, v34
	v_exp_f32_e32 v34, v34
	v_cndmask_b32_e64 v2, 0, v2, s[0:1]
	v_cmp_lt_f32_e64 s[0:1], s2, v6
	v_sub_f32_e32 v6, v6, v22
	v_mul_f32_e32 v6, 0x3fb8aa3b, v6
	v_exp_f32_e32 v6, v6
	v_add_f32_e32 v18, 0, v2
	v_cndmask_b32_e32 v9, v66, v9, vcc
	v_cndmask_b32_e64 v13, v66, v13, s[38:39]
	v_cndmask_b32_e64 v10, 0, v6, s[0:1]
	v_sub_f32_e32 v6, v45, v22
	v_mul_f32_e32 v6, 0x3fb8aa3b, v6
	v_exp_f32_e32 v6, v6
	v_cmp_lt_f32_e64 s[0:1], s2, v45
	v_add_f32_e32 v18, v10, v18
	v_cndmask_b32_e64 v17, v66, v17, s[40:41]
	v_cndmask_b32_e64 v6, 0, v6, s[0:1]
	v_cmp_lt_f32_e64 s[0:1], s2, v14
	v_sub_f32_e32 v14, v14, v22
	v_mul_f32_e32 v14, 0x3fb8aa3b, v14
	v_exp_f32_e32 v14, v14
	v_add_f32_e32 v30, v6, v18
	v_cndmask_b32_e64 v21, v66, v21, s[42:43]
	v_cndmask_b32_e64 v29, v66, v29, s[46:47]
	v_cndmask_b32_e64 v18, 0, v14, s[0:1]
	v_sub_f32_e32 v14, v44, v22
	v_mul_f32_e32 v14, 0x3fb8aa3b, v14
	v_exp_f32_e32 v14, v14
	v_cmp_lt_f32_e64 s[0:1], s2, v44
	v_add_f32_e32 v30, v18, v30
	v_cndmask_b32_e64 v33, v66, v33, s[48:49]
	v_cndmask_b32_e64 v14, 0, v14, s[0:1]
	v_cmp_lt_f32_e64 s[0:1], s2, v46
	v_add_f32_e32 v30, v14, v30
	s_nop 0
	v_cndmask_b32_e64 v34, 0, v34, s[0:1]
	v_cmp_lt_f32_e64 s[0:1], s2, v26
	v_sub_f32_e32 v26, v26, v22
	v_mul_f32_e32 v26, 0x3fb8aa3b, v26
	v_exp_f32_e32 v26, v26
	v_add_f32_e32 v44, v34, v30
	s_barrier
; __device__ __forceinline__ float fexp(float x) { return __builtin_amdgcn_exp2f(x * 1.4426950408889634f); }
; #define SHX(v, m) shx_((v), (m), lane)
; __device__ void swa_item(const Params& p, int item) {
;     ...
;   _Pragma("unroll") for (int jj = 0; jj < 4; ++jj) {
;     const int qi = w * 16 + q * 4 + jj;
;     float m = -1e30f;
;     _Pragma("unroll") for (int ci = 0; ci < 9; ++ci) {
;       int kj = (w + ci) * 16 + c; int dist = qi + 128 - kj;
;       bool valid = (dist >= 0) && (dist <= 128) && (qb > 0 || kj >= 128);
;       float s = valid ? S[ci][jj] : -1e30f;
;       S[ci][jj] = s; m = fmaxf(m, s);
;     }
;     m = fmaxf(m, SHX(m, 1)); m = fmaxf(m, SHX(m, 2)); m = fmaxf(m, SHX(m, 4)); m = fmaxf(m, SHX(m, 8));
;     float l = 0.f;
;     _Pragma("unroll") for (int ci = 0; ci < 9; ++ci) {
;       float s = S[ci][jj];
;       float pv = (s > -1e29f) ? fexp(s - m) : 0.f;
;       S[ci][jj] = pv; l += pv;
;     }
;     l += SHX(l, 1); l += SHX(l, 2); l += SHX(l, 4); l += SHX(l, 8);
;     mx[jj] = m; ls[jj] = l;
;   }
	global_load_dword v243, v240, s[52:53]
	global_load_dword v243, v241, s[52:53]
	global_load_dword v243, v242, s[52:53]
	v_cndmask_b32_e64 v30, 0, v26, s[0:1]
	v_add_f32_e32 v26, v30, v44
	v_sub_f32_e32 v44, v47, v22
	v_mul_f32_e32 v44, 0x3fb8aa3b, v44
	v_exp_f32_e32 v44, v44
	v_cmp_lt_f32_e64 s[0:1], s2, v47
	s_nop 1
	v_cndmask_b32_e64 v45, 0, v44, s[0:1]
	v_sub_f32_e32 v44, v48, v22
	v_mul_f32_e32 v44, 0x3fb8aa3b, v44
	v_exp_f32_e32 v44, v44
	v_cmp_lt_f32_e64 s[0:1], s2, v48
	v_add_f32_e32 v26, v45, v26
	v_cndmask_b32_e64 v48, v66, v11, s[38:39]
	v_cndmask_b32_e64 v44, 0, v44, s[0:1]
	v_add_f32_e32 v26, v44, v26
	s_waitcnt lgkmcnt(0)
	s_nop 1
	v_add_f32_dpp v26, v26, v26 row_ror:1 row_mask:0xf bank_mask:0xf
	s_waitcnt lgkmcnt(0)
	s_nop 1
	v_add_f32_dpp v26, v26, v26 row_ror:2 row_mask:0xf bank_mask:0xf
	s_waitcnt lgkmcnt(0)
	s_nop 1
	v_add_f32_dpp v26, v26, v26 row_ror:4 row_mask:0xf bank_mask:0xf
	s_waitcnt lgkmcnt(0)
	s_nop 1
	v_add_f32_dpp v26, v26, v26 row_ror:8 row_mask:0xf bank_mask:0xf
	v_or_b32_e32 v46, 1, v43
	v_sub_u32_e32 v47, v46, v53
	v_cmp_gt_u32_e64 s[0:1], s18, v47
	s_and_b64 s[0:1], s[0:1], s[12:13]
	s_nop 0
	v_cndmask_b32_e64 v3, v66, v3, s[0:1]
	v_max_f32_e32 v47, v3, v3
	v_max_f32_e32 v47, 0xf149f2ca, v47
	v_max3_f32 v11, v47, v7, v48
	v_cndmask_b32_e64 v47, v66, v19, s[42:43]
	v_sub_u32_e32 v19, v46, v59
	v_cmp_gt_u32_e64 s[0:1], s18, v19
	v_max3_f32 v11, v11, v15, v47
	s_and_b64 s[0:1], s[0:1], s[14:15]
	v_max3_f32 v11, v11, v49, v27
	v_cndmask_b32_e64 v35, v66, v35, s[0:1]
	v_max3_f32 v11, v11, v54, v35
	v_cmp_lt_f32_e64 s[0:1], s2, v3
	s_waitcnt lgkmcnt(0)
	s_nop 1
	v_max_f32_dpp v11, v11, v11 row_ror:1 row_mask:0xf bank_mask:0xf
	s_waitcnt lgkmcnt(0)
	s_nop 1
	v_max_f32_dpp v11, v11, v11 row_ror:2 row_mask:0xf bank_mask:0xf
	s_waitcnt lgkmcnt(0)
	s_nop 1
	v_max_f32_dpp v11, v11, v11 row_ror:4 row_mask:0xf bank_mask:0xf
	s_waitcnt lgkmcnt(0)
	s_nop 1
	v_max_f32_dpp v23, v11, v11 row_ror:8 row_mask:0xf bank_mask:0xf
	v_sub_f32_e32 v3, v3, v23
	v_mul_f32_e32 v3, 0x3fb8aa3b, v3
	v_exp_f32_e32 v3, v3
	v_sub_f32_e32 v46, v49, v23
	v_mul_f32_e32 v46, 0x3fb8aa3b, v46
	v_exp_f32_e32 v46, v46
	v_cndmask_b32_e64 v3, 0, v3, s[0:1]
	v_cmp_lt_f32_e64 s[0:1], s2, v7
	v_sub_f32_e32 v7, v7, v23
	v_mul_f32_e32 v7, 0x3fb8aa3b, v7
	v_exp_f32_e32 v7, v7
	v_add_f32_e32 v19, 0, v3
	v_cndmask_b32_e64 v11, 0, v7, s[0:1]
	v_sub_f32_e32 v7, v48, v23
	v_mul_f32_e32 v7, 0x3fb8aa3b, v7
	v_exp_f32_e32 v7, v7
	v_cmp_lt_f32_e64 s[0:1], s2, v48
	v_add_f32_e32 v19, v11, v19
	s_nop 0
	v_cndmask_b32_e64 v7, 0, v7, s[0:1]
	v_cmp_lt_f32_e64 s[0:1], s2, v15
	v_sub_f32_e32 v15, v15, v23
	v_mul_f32_e32 v15, 0x3fb8aa3b, v15
	v_exp_f32_e32 v15, v15
	v_add_f32_e32 v31, v7, v19
	v_cndmask_b32_e64 v19, 0, v15, s[0:1]
	v_sub_f32_e32 v15, v47, v23
	v_mul_f32_e32 v15, 0x3fb8aa3b, v15
	v_exp_f32_e32 v15, v15
	v_cmp_lt_f32_e64 s[0:1], s2, v47
	v_add_f32_e32 v31, v19, v31
	s_nop 0
	v_cndmask_b32_e64 v15, 0, v15, s[0:1]
	v_cmp_lt_f32_e64 s[0:1], s2, v49
	v_add_f32_e32 v31, v15, v31
	s_nop 0
	v_cndmask_b32_e64 v46, 0, v46, s[0:1]
	v_cmp_lt_f32_e64 s[0:1], s2, v27
	v_sub_f32_e32 v27, v27, v23
	v_mul_f32_e32 v27, 0x3fb8aa3b, v27
	v_exp_f32_e32 v27, v27
	v_add_f32_e32 v47, v46, v31
	v_cndmask_b32_e64 v31, 0, v27, s[0:1]
	v_add_f32_e32 v27, v31, v47
	v_sub_f32_e32 v47, v54, v23
	v_mul_f32_e32 v47, 0x3fb8aa3b, v47
	v_exp_f32_e32 v47, v47
	v_cmp_lt_f32_e64 s[0:1], s2, v54
	v_cndmask_b32_e64 v54, v66, v24, s[44:45]
	s_nop 0
	v_cndmask_b32_e64 v47, 0, v47, s[0:1]
	v_cmp_lt_f32_e64 s[0:1], s2, v35
	v_sub_f32_e32 v35, v35, v23
	v_mul_f32_e32 v35, 0x3fb8aa3b, v35
	v_exp_f32_e32 v35, v35
	v_add_f32_e32 v27, v47, v27
	v_cndmask_b32_e64 v35, 0, v35, s[0:1]
	v_add_f32_e32 v27, v35, v27
	s_waitcnt lgkmcnt(0)
	s_nop 1
	v_add_f32_dpp v27, v27, v27 row_ror:1 row_mask:0xf bank_mask:0xf
	s_waitcnt lgkmcnt(0)
	s_nop 1
	v_add_f32_dpp v27, v27, v27 row_ror:2 row_mask:0xf bank_mask:0xf
	s_waitcnt lgkmcnt(0)
	s_nop 1
	v_add_f32_dpp v27, v27, v27 row_ror:4 row_mask:0xf bank_mask:0xf
	s_waitcnt lgkmcnt(0)
	s_nop 1
	v_add_f32_dpp v27, v27, v27 row_ror:8 row_mask:0xf bank_mask:0xf
	v_or_b32_e32 v48, 2, v43
	v_sub_u32_e32 v49, v48, v53
	v_cmp_gt_u32_e64 s[0:1], s18, v49
	s_and_b64 s[0:1], s[0:1], s[12:13]
	v_sub_u32_e32 v32, v48, v59
	v_cndmask_b32_e64 v4, v66, v4, s[0:1]
	v_max_f32_e32 v49, v4, v4
	v_max_f32_e32 v49, 0xf149f2ca, v49
	v_max3_f32 v49, v49, v8, v12
	v_cmp_gt_u32_e64 s[0:1], s18, v32
	v_max3_f32 v49, v49, v16, v20
	s_and_b64 s[0:1], s[0:1], s[14:15]
	v_max3_f32 v24, v49, v54, v28
	v_cndmask_b32_e64 v61, v66, v36, s[0:1]
	v_max3_f32 v24, v24, v60, v61
	v_cmp_lt_f32_e64 s[0:1], s2, v4
	v_or_b32_e32 v43, 3, v43
	v_sub_u32_e32 v53, v43, v53
	v_sub_u32_e32 v43, v43, v59
	s_waitcnt lgkmcnt(0)
	s_nop 1
	v_max_f32_dpp v24, v24, v24 row_ror:1 row_mask:0xf bank_mask:0xf
	v_cmp_gt_u32_e32 vcc, s18, v43
	s_and_b64 vcc, vcc, s[14:15]
	s_waitcnt lgkmcnt(0)
	s_nop 1
	v_max_f32_dpp v24, v24, v24 row_ror:2 row_mask:0xf bank_mask:0xf
	v_cndmask_b32_e32 v37, v66, v37, vcc
	s_waitcnt lgkmcnt(0)
	s_nop 1
	v_max_f32_dpp v24, v24, v24 row_ror:4 row_mask:0xf bank_mask:0xf
	s_waitcnt lgkmcnt(0)
; __device__ __forceinline__ float fexp(float x) { return __builtin_amdgcn_exp2f(x * 1.4426950408889634f); }
; #define SHX(v, m) shx_((v), (m), lane)
; __device__ void swa_item(const Params& p, int item) {
;     ...
;   _Pragma("unroll") for (int jj = 0; jj < 4; ++jj) {
;     const int qi = w * 16 + q * 4 + jj;
;     float m = -1e30f;
;     _Pragma("unroll") for (int ci = 0; ci < 9; ++ci) {
;       int kj = (w + ci) * 16 + c; int dist = qi + 128 - kj;
;       bool valid = (dist >= 0) && (dist <= 128) && (qb > 0 || kj >= 128);
;       float s = valid ? S[ci][jj] : -1e30f;
;       S[ci][jj] = s; m = fmaxf(m, s);
;     }
;     m = fmaxf(m, SHX(m, 1)); m = fmaxf(m, SHX(m, 2)); m = fmaxf(m, SHX(m, 4)); m = fmaxf(m, SHX(m, 8));
;     float l = 0.f;
;     _Pragma("unroll") for (int ci = 0; ci < 9; ++ci) {
;       float s = S[ci][jj];
;       float pv = (s > -1e29f) ? fexp(s - m) : 0.f;
;       S[ci][jj] = pv; l += pv;
;     }
;     l += SHX(l, 1); l += SHX(l, 2); l += SHX(l, 4); l += SHX(l, 8);
;     mx[jj] = m; ls[jj] = l;
;   }
	s_nop 1
	v_max_f32_dpp v24, v24, v24 row_ror:8 row_mask:0xf bank_mask:0xf
	v_sub_f32_e32 v4, v4, v24
	v_mul_f32_e32 v4, 0x3fb8aa3b, v4
	v_exp_f32_e32 v4, v4
	s_nop 0
	v_cndmask_b32_e64 v4, 0, v4, s[0:1]
	v_cmp_lt_f32_e64 s[0:1], s2, v8
	v_sub_f32_e32 v8, v8, v24
	v_mul_f32_e32 v8, 0x3fb8aa3b, v8
	v_exp_f32_e32 v8, v8
	v_add_f32_e32 v32, 0, v4
	v_cndmask_b32_e64 v8, 0, v8, s[0:1]
	v_cmp_lt_f32_e64 s[0:1], s2, v12
	v_sub_f32_e32 v12, v12, v24
	v_mul_f32_e32 v12, 0x3fb8aa3b, v12
	v_exp_f32_e32 v12, v12
	v_add_f32_e32 v32, v8, v32
	v_cndmask_b32_e64 v12, 0, v12, s[0:1]
	v_cmp_lt_f32_e64 s[0:1], s2, v16
	v_sub_f32_e32 v16, v16, v24
	v_mul_f32_e32 v16, 0x3fb8aa3b, v16
	v_exp_f32_e32 v16, v16
	v_add_f32_e32 v32, v12, v32
	v_cndmask_b32_e64 v16, 0, v16, s[0:1]
	v_cmp_lt_f32_e64 s[0:1], s2, v20
	v_sub_f32_e32 v20, v20, v24
	v_mul_f32_e32 v20, 0x3fb8aa3b, v20
	v_exp_f32_e32 v20, v20
	v_add_f32_e32 v36, v16, v32
	v_cndmask_b32_e64 v32, 0, v20, s[0:1]
	v_add_f32_e32 v20, v32, v36
	v_sub_f32_e32 v36, v54, v24
	v_mul_f32_e32 v36, 0x3fb8aa3b, v36
	v_exp_f32_e32 v36, v36
	v_cmp_lt_f32_e64 s[0:1], s2, v54
	s_nop 1
	v_cndmask_b32_e64 v49, 0, v36, s[0:1]
	v_cmp_lt_f32_e64 s[0:1], s2, v28
	v_sub_f32_e32 v28, v28, v24
	v_mul_f32_e32 v28, 0x3fb8aa3b, v28
	v_exp_f32_e32 v28, v28
	v_add_f32_e32 v20, v49, v20
	v_cndmask_b32_e64 v48, 0, v28, s[0:1]
	v_sub_f32_e32 v28, v60, v24
	v_mul_f32_e32 v28, 0x3fb8aa3b, v28
	v_exp_f32_e32 v28, v28
	v_cmp_lt_f32_e64 s[0:1], s2, v60
	v_add_f32_e32 v20, v48, v20
	s_nop 0
	v_cndmask_b32_e64 v36, 0, v28, s[0:1]
	v_add_f32_e32 v28, v36, v20
	v_sub_f32_e32 v20, v61, v24
	v_mul_f32_e32 v20, 0x3fb8aa3b, v20
	v_exp_f32_e32 v20, v20
	v_cmp_lt_f32_e64 s[0:1], s2, v61
	s_nop 1
	v_cndmask_b32_e64 v20, 0, v20, s[0:1]
	v_add_f32_e32 v28, v20, v28
	v_cmp_gt_u32_e64 s[0:1], s18, v53
	s_and_b64 s[0:1], s[0:1], s[12:13]
	s_waitcnt lgkmcnt(0)
	s_nop 1
	v_add_f32_dpp v28, v28, v28 row_ror:1 row_mask:0xf bank_mask:0xf
	v_cndmask_b32_e64 v5, v66, v5, s[0:1]
	v_max_f32_e32 v53, v5, v5
	v_max_f32_e32 v53, 0xf149f2ca, v53
	v_max3_f32 v53, v53, v9, v13
	s_waitcnt lgkmcnt(0)
	s_nop 1
	v_add_f32_dpp v28, v28, v28 row_ror:2 row_mask:0xf bank_mask:0xf
	v_max3_f32 v53, v53, v17, v21
	v_cmp_lt_f32_e32 vcc, s2, v5
	s_movk_i32 s0, 0x540
	s_waitcnt lgkmcnt(0)
	s_nop 1
	v_add_f32_dpp v28, v28, v28 row_ror:4 row_mask:0xf bank_mask:0xf
	s_waitcnt lgkmcnt(0)
	s_nop 1
	v_add_f32_dpp v28, v28, v28 row_ror:8 row_mask:0xf bank_mask:0xf
	v_cndmask_b32_e64 v54, v66, v25, s[44:45]
	v_max3_f32 v25, v53, v54, v29
	v_max3_f32 v25, v25, v33, v37
	s_waitcnt lgkmcnt(0)
	s_nop 1
	v_max_f32_dpp v25, v25, v25 row_ror:1 row_mask:0xf bank_mask:0xf
	s_waitcnt lgkmcnt(0)
	s_nop 1
	v_max_f32_dpp v25, v25, v25 row_ror:2 row_mask:0xf bank_mask:0xf
	s_waitcnt lgkmcnt(0)
	s_nop 1
	v_max_f32_dpp v25, v25, v25 row_ror:4 row_mask:0xf bank_mask:0xf
	s_waitcnt lgkmcnt(0)
	s_nop 1
	v_max_f32_dpp v25, v25, v25 row_ror:8 row_mask:0xf bank_mask:0xf
	v_sub_f32_e32 v5, v5, v25
	v_mul_f32_e32 v5, 0x3fb8aa3b, v5
	v_exp_f32_e32 v5, v5
	v_sub_f32_e32 v53, v54, v25
	v_mul_f32_e32 v53, 0x3fb8aa3b, v53
	v_exp_f32_e32 v53, v53
	v_cndmask_b32_e32 v5, 0, v5, vcc
	v_cmp_lt_f32_e32 vcc, s2, v9
	v_sub_f32_e32 v9, v9, v25
	v_mul_f32_e32 v9, 0x3fb8aa3b, v9
	v_exp_f32_e32 v9, v9
	v_add_f32_e32 v43, 0, v5
	v_cndmask_b32_e32 v9, 0, v9, vcc
	v_cmp_lt_f32_e32 vcc, s2, v13
	v_sub_f32_e32 v13, v13, v25
	v_mul_f32_e32 v13, 0x3fb8aa3b, v13
	v_exp_f32_e32 v13, v13
	v_add_f32_e32 v43, v9, v43
	v_cndmask_b32_e32 v13, 0, v13, vcc
	v_cmp_lt_f32_e32 vcc, s2, v17
	v_sub_f32_e32 v17, v17, v25
	v_mul_f32_e32 v17, 0x3fb8aa3b, v17
	v_exp_f32_e32 v17, v17
	v_add_f32_e32 v43, v13, v43
	v_cndmask_b32_e32 v17, 0, v17, vcc
	v_cmp_lt_f32_e32 vcc, s2, v21
	v_sub_f32_e32 v21, v21, v25
	v_mul_f32_e32 v21, 0x3fb8aa3b, v21
	v_exp_f32_e32 v21, v21
	v_add_f32_e32 v43, v17, v43
	v_cndmask_b32_e32 v21, 0, v21, vcc
	v_cmp_lt_f32_e32 vcc, s2, v54
	v_add_f32_e32 v43, v21, v43
	s_nop 0
	v_cndmask_b32_e32 v53, 0, v53, vcc
	v_cmp_lt_f32_e32 vcc, s2, v29
	v_sub_f32_e32 v29, v29, v25
	v_mul_f32_e32 v29, 0x3fb8aa3b, v29
	v_exp_f32_e32 v29, v29
	v_add_f32_e32 v43, v53, v43
	v_cndmask_b32_e32 v54, 0, v29, vcc
	v_cmp_lt_f32_e32 vcc, s2, v33
	v_sub_f32_e32 v33, v33, v25
	v_mul_f32_e32 v33, 0x3fb8aa3b, v33
	v_exp_f32_e32 v33, v33
	v_add_f32_e32 v29, v54, v43
	v_or_b32_e32 v43, 1, v38
	v_cndmask_b32_e32 v33, 0, v33, vcc
	v_cmp_lt_f32_e32 vcc, s2, v37
	v_sub_f32_e32 v37, v37, v25
	v_mul_f32_e32 v37, 0x3fb8aa3b, v37
	v_exp_f32_e32 v37, v37
	v_add_f32_e32 v29, v33, v29
	s_movk_i32 s2, 0xc0
	v_cndmask_b32_e32 v37, 0, v37, vcc
	v_add_f32_e32 v29, v37, v29
	s_waitcnt lgkmcnt(0)
	s_nop 1
	v_add_f32_dpp v29, v29, v29 row_ror:1 row_mask:0xf bank_mask:0xf
	s_waitcnt lgkmcnt(0)
	s_nop 1
	v_add_f32_dpp v29, v29, v29 row_ror:2 row_mask:0xf bank_mask:0xf
	v_bfe_u32 v41, v2, 16, 1
	v_add3_u32 v2, v2, v41, s72
	v_mul_u32_u24_e32 v41, 0x540, v56
	s_waitcnt lgkmcnt(0)
	s_nop 1
	v_add_f32_dpp v29, v29, v29 row_ror:4 row_mask:0xf bank_mask:0xf
	s_waitcnt lgkmcnt(0)
; __device__ __forceinline__ float frcp(float x) { return __builtin_amdgcn_rcpf(x); }
; #define SHX(v, m) shx_((v), (m), lane)
; __device__ void swa_item(const Params& p, int item) {
;     ...
;     l += SHX(l, 1); l += SHX(l, 2); l += SHX(l, 4); l += SHX(l, 8);
;     mx[jj] = m; ls[jj] = l;
;   }
;   __syncthreads();
;   _Pragma("unroll") for (int ci = 0; ci < 9; ++ci) _Pragma("unroll") for (int jj = 0; jj < 4; ++jj) Pl[(q * 4 + jj) * 168 + ci * 16 + c] = f2bf(S[ci][jj]);
;   _Pragma("unroll") for (int jj = 0; jj < 4; ++jj) Pl[(q * 4 + jj) * 168 + 144 + c] = 0;
;   asm volatile("s_waitcnt lgkmcnt(0)" ::: "memory");
;   bf16x8 pf[5];
;   _Pragma("unroll") for (int kk = 0; kk < 5; ++kk) pf[kk] = *(const bf16x8*)(Pl + c * 168 + kk * 32 + q * 8);
;   asm volatile("s_waitcnt lgkmcnt(0)" ::: "memory");
;   float il[4];
;   _Pragma("unroll") for (int jj = 0; jj < 4; ++jj) il[jj] = frcp(ls[jj]);
;   bfu* Ow = Pl;
;   _Pragma("unroll") for (int dt = 0; dt < 8; ++dt) {
;     f32x4 a = (f32x4){0.f, 0.f, 0.f, 0.f};
;     _Pragma("unroll") for (int kk = 0; kk < 5; ++kk) {
;       const int k0_ = w * 16 + kk * 32 + q * 8; const int ch_ = k0_ >> 3;
;       const int chp_ = (ch_ < 32) ? (ch_ ^ (((dt * 16 + c) >> 3) & 15)) : ch_;
;       bf16x8 vf = *(const bf16x8*)(Vt + (dt * 16 + c) * 280 + chp_ * 8);
;       a = __builtin_amdgcn_mfma_f32_16x16x32_bf16(pf[kk], vf, a, 0, 0, 0);
	s_nop 1
	v_add_f32_dpp v29, v29, v29 row_ror:8 row_mask:0xf bank_mask:0xf
	v_lshlrev_b32_e32 v39, 1, v55
	v_add_u32_e32 v40, v57, v39
	v_mad_u32_u24 v42, v56, s0, v40
	ds_write_b16_d16_hi v42, v2
	v_bfe_u32 v2, v3, 16, 1
	s_movk_i32 s0, 0x150
	v_add3_u32 v2, v3, v2, s72
	v_mad_u32_u24 v59, v43, s0, v40
	ds_write_b16_d16_hi v59, v2
	v_bfe_u32 v2, v4, 16, 1
	v_add3_u32 v2, v4, v2, s72
	v_mad_u32_u24 v4, v43, s0, s0
	v_add_u32_e32 v60, v40, v4
	ds_write_b16_d16_hi v60, v2
	v_bfe_u32 v2, v5, 16, 1
	v_add3_u32 v2, v5, v2, s72
	v_mov_b32_e32 v5, 0x2a0
	v_mad_u32_u24 v5, v43, s0, v5
	v_add_u32_e32 v61, v40, v5
	ds_write_b16_d16_hi v61, v2
	v_bfe_u32 v2, v10, 16, 1
	v_add3_u32 v2, v10, v2, s72
	ds_write_b16_d16_hi v42, v2 offset:32
	v_bfe_u32 v2, v11, 16, 1
	v_add3_u32 v2, v11, v2, s72
	ds_write_b16_d16_hi v59, v2 offset:32
	v_bfe_u32 v2, v8, 16, 1
	v_add3_u32 v2, v8, v2, s72
	ds_write_b16_d16_hi v60, v2 offset:32
	v_bfe_u32 v2, v9, 16, 1
	v_add3_u32 v2, v9, v2, s72
	ds_write_b16_d16_hi v61, v2 offset:32
	v_bfe_u32 v2, v6, 16, 1
	v_add3_u32 v2, v6, v2, s72
	ds_write_b16_d16_hi v42, v2 offset:64
	v_bfe_u32 v2, v7, 16, 1
	v_add3_u32 v2, v7, v2, s72
	ds_write_b16_d16_hi v59, v2 offset:64
	v_bfe_u32 v2, v12, 16, 1
	v_add3_u32 v2, v12, v2, s72
	ds_write_b16_d16_hi v60, v2 offset:64
	v_bfe_u32 v2, v13, 16, 1
	v_add3_u32 v2, v13, v2, s72
	ds_write_b16_d16_hi v61, v2 offset:64
	v_bfe_u32 v2, v18, 16, 1
	v_add3_u32 v2, v18, v2, s72
	ds_write_b16_d16_hi v42, v2 offset:96
	v_bfe_u32 v2, v19, 16, 1
	v_add3_u32 v2, v19, v2, s72
	ds_write_b16_d16_hi v59, v2 offset:96
	v_bfe_u32 v2, v16, 16, 1
	v_add3_u32 v2, v16, v2, s72
	ds_write_b16_d16_hi v60, v2 offset:96
	v_bfe_u32 v2, v17, 16, 1
	v_add3_u32 v2, v17, v2, s72
	ds_write_b16_d16_hi v61, v2 offset:96
	v_bfe_u32 v2, v14, 16, 1
	v_add3_u32 v2, v14, v2, s72
	ds_write_b16_d16_hi v42, v2 offset:128
	v_bfe_u32 v2, v15, 16, 1
	v_add3_u32 v2, v15, v2, s72
	ds_write_b16_d16_hi v59, v2 offset:128
	v_bfe_u32 v2, v32, 16, 1
	v_add3_u32 v2, v32, v2, s72
	ds_write_b16_d16_hi v60, v2 offset:128
	v_bfe_u32 v2, v21, 16, 1
	v_add3_u32 v2, v21, v2, s72
	ds_write_b16_d16_hi v61, v2 offset:128
	v_bfe_u32 v2, v34, 16, 1
	v_add3_u32 v2, v34, v2, s72
	ds_write_b16_d16_hi v42, v2 offset:160
	v_bfe_u32 v2, v46, 16, 1
	v_add3_u32 v2, v46, v2, s72
	ds_write_b16_d16_hi v59, v2 offset:160
	v_bfe_u32 v2, v49, 16, 1
	v_add3_u32 v2, v49, v2, s72
	ds_write_b16_d16_hi v60, v2 offset:160
	v_bfe_u32 v2, v53, 16, 1
	v_add3_u32 v2, v53, v2, s72
	ds_write_b16_d16_hi v61, v2 offset:160
	v_bfe_u32 v2, v30, 16, 1
	v_add3_u32 v2, v30, v2, s72
	ds_write_b16_d16_hi v42, v2 offset:192
	v_bfe_u32 v2, v31, 16, 1
	v_add3_u32 v2, v31, v2, s72
	ds_write_b16_d16_hi v59, v2 offset:192
	v_bfe_u32 v2, v48, 16, 1
	v_add3_u32 v2, v48, v2, s72
	ds_write_b16_d16_hi v60, v2 offset:192
	v_bfe_u32 v2, v54, 16, 1
	v_add3_u32 v2, v54, v2, s72
	ds_write_b16_d16_hi v61, v2 offset:192
	v_bfe_u32 v2, v45, 16, 1
	v_add3_u32 v2, v45, v2, s72
	ds_write_b16_d16_hi v42, v2 offset:224
	v_bfe_u32 v2, v47, 16, 1
	v_add3_u32 v2, v47, v2, s72
	ds_write_b16_d16_hi v59, v2 offset:224
	v_bfe_u32 v2, v36, 16, 1
	v_add3_u32 v2, v36, v2, s72
	ds_write_b16_d16_hi v60, v2 offset:224
	v_bfe_u32 v2, v33, 16, 1
	v_add3_u32 v2, v33, v2, s72
	ds_write_b16_d16_hi v61, v2 offset:224
	v_bfe_u32 v2, v44, 16, 1
	v_add3_u32 v2, v44, v2, s72
	ds_write_b16_d16_hi v42, v2 offset:256
	v_bfe_u32 v2, v35, 16, 1
	v_add3_u32 v2, v35, v2, s72
	ds_write_b16_d16_hi v59, v2 offset:256
	v_bfe_u32 v2, v20, 16, 1
	v_add3_u32 v2, v20, v2, s72
	ds_write_b16_d16_hi v60, v2 offset:256
	v_bfe_u32 v2, v37, 16, 1
	v_add3_u32 v2, v37, v2, s72
	v_mul_u32_u24_e32 v3, 0x150, v43
	ds_write_b16_d16_hi v61, v2 offset:256
	v_add3_u32 v2, v57, v41, v39
	ds_write_b16 v2, v1 offset:288
	v_add3_u32 v2, v57, v3, v39
	ds_write_b16 v2, v1 offset:288
	v_add3_u32 v2, v57, v4, v39
	v_lshl_add_u32 v45, v56, 3, v58
	s_movk_i32 s0, 0x100
	ds_write_b16 v2, v1 offset:288
	v_add3_u32 v2, v57, v5, v39
	v_and_b32_e32 v46, 8, v50
	v_cmp_gt_i32_e32 vcc, s0, v45
	ds_write_b16 v2, v1 offset:288
	v_mul_u32_u24_e32 v2, 0x150, v55
	v_cndmask_b32_e32 v30, 0, v46, vcc
	s_waitcnt lgkmcnt(0)
	v_add3_u32 v2, v57, v2, v52
	v_mad_u32_u24 v47, v55, s25, 0
	v_xor_b32_e32 v30, v30, v45
	ds_read_b128 v[18:21], v2
	ds_read_b128 v[14:17], v2 offset:64
	ds_read_b128 v[10:13], v2 offset:128
	ds_read_b128 v[6:9], v2 offset:192
	ds_read_b128 v[2:5], v2 offset:256
	s_waitcnt lgkmcnt(0)
	v_lshl_add_u32 v30, v30, 1, v47
	s_movk_i32 s0, 0xe0
	ds_read_b128 v[30:33], v30
	v_cmp_gt_i32_e64 s[0:1], s0, v45
	v_add_u32_e32 v48, 32, v45
	v_cmp_gt_i32_e64 s[38:39], s2, v45
	v_cndmask_b32_e64 v34, 0, v46, s[0:1]
	v_xor_b32_e32 v34, v34, v48
	v_lshl_add_u32 v34, v34, 1, v47
	ds_read_b128 v[34:37], v34
	s_waitcnt lgkmcnt(1)
	v_mfma_f32_16x16x32_bf16 v[30:33], v[18:21], v[30:33], 0
	v_add_u32_e32 v49, 64, v45
	s_movk_i32 s2, 0xa0
	v_cmp_gt_i32_e64 s[40:41], s2, v45
	s_waitcnt lgkmcnt(0)
	v_mfma_f32_16x16x32_bf16 v[30:33], v[14:17], v[34:37], v[30:33]
	v_cndmask_b32_e64 v34, 0, v46, s[38:39]
	v_xor_b32_e32 v34, v34, v49
	v_lshl_add_u32 v34, v34, 1, v47
	ds_read_b128 v[34:37], v34
	v_add_u32_e32 v50, 0x60, v45
	s_waitcnt lgkmcnt(0)
	v_mfma_f32_16x16x32_bf16 v[30:33], v[10:13], v[34:37], v[30:33]
	v_cndmask_b32_e64 v34, 0, v46, s[40:41]
	v_xor_b32_e32 v34, v34, v50
	v_lshl_add_u32 v34, v34, 1, v47
	ds_read_b128 v[34:37], v34
	s_movk_i32 s2, 0x80
	v_cmp_gt_i32_e64 s[42:43], s2, v45
	s_waitcnt lgkmcnt(0)
	v_mfma_f32_16x16x32_bf16 v[30:33], v[6:9], v[34:37], v[30:33]
	v_add_u32_e32 v52, 0x80, v45
	v_cndmask_b32_e64 v34, 0, v46, s[42:43]
	v_xor_b32_e32 v34, v34, v52
	v_lshl_add_u32 v34, v34, 1, v47
	ds_read_b128 v[34:37], v34
	v_rcp_f32_e32 v39, v26
	s_waitcnt lgkmcnt(0)
; __device__ __forceinline__ float frcp(float x) { return __builtin_amdgcn_rcpf(x); }
; __device__ void swa_item(const Params& p, int item) {
;     ...
;   _Pragma("unroll") for (int jj = 0; jj < 4; ++jj) il[jj] = frcp(ls[jj]);
;   bfu* Ow = Pl;
;   _Pragma("unroll") for (int dt = 0; dt < 8; ++dt) {
;     f32x4 a = (f32x4){0.f, 0.f, 0.f, 0.f};
;     _Pragma("unroll") for (int kk = 0; kk < 5; ++kk) {
;       const int k0_ = w * 16 + kk * 32 + q * 8; const int ch_ = k0_ >> 3;
;       const int chp_ = (ch_ < 32) ? (ch_ ^ (((dt * 16 + c) >> 3) & 15)) : ch_;
;       bf16x8 vf = *(const bf16x8*)(Vt + (dt * 16 + c) * 280 + chp_ * 8);
;       a = __builtin_amdgcn_mfma_f32_16x16x32_bf16(pf[kk], vf, a, 0, 0, 0);
;     }
;     _Pragma("unroll") for (int jj = 0; jj < 4; ++jj) Ow[(q * 4 + jj) * 136 + dt * 16 + c] = f2bf(a[jj] * il[jj]);
	v_mfma_f32_16x16x32_bf16 v[30:33], v[2:5], v[34:37], v[30:33]
	v_rcp_f32_e32 v41, v27
	s_movk_i32 s2, 0x440
	v_rcp_f32_e32 v42, v28
	s_nop 4
	v_mul_f32_e32 v30, v39, v30
	v_bfe_u32 v34, v30, 16, 1
	v_add3_u32 v30, v30, v34, s72
	v_mad_u32_u24 v53, v56, s2, v40
	ds_write_b16_d16_hi v53, v30
	v_mul_f32_e32 v30, v41, v31
	v_bfe_u32 v31, v30, 16, 1
	v_rcp_f32_e32 v44, v29
	v_add3_u32 v30, v30, v31, s72
	v_mad_u32_u24 v40, v43, s3, v40
	ds_write_b16_d16_hi v40, v30
	v_mul_f32_e32 v30, v42, v32
	v_bfe_u32 v31, v30, 16, 1
	v_add3_u32 v30, v30, v31, s72
	ds_write_b16_d16_hi v40, v30 offset:272
	v_mul_f32_e32 v30, v44, v33
	v_bfe_u32 v31, v30, 16, 1
	v_add3_u32 v30, v30, v31, s72
	v_or_b32_e32 v43, 16, v46
	ds_write_b16_d16_hi v40, v30 offset:544
	v_cndmask_b32_e32 v30, 0, v43, vcc
	v_xor_b32_e32 v30, v30, v45
	v_lshl_add_u32 v30, v30, 1, v47
	ds_read_b128 v[30:33], v30 offset:8960
	v_cndmask_b32_e64 v34, 0, v43, s[0:1]
	v_xor_b32_e32 v34, v34, v48
	v_lshl_add_u32 v34, v34, 1, v47
	ds_read_b128 v[34:37], v34 offset:8960
	s_waitcnt lgkmcnt(1)
	v_mfma_f32_16x16x32_bf16 v[30:33], v[18:21], v[30:33], 0
	s_waitcnt lgkmcnt(0)
	v_mfma_f32_16x16x32_bf16 v[30:33], v[14:17], v[34:37], v[30:33]
	v_cndmask_b32_e64 v34, 0, v43, s[38:39]
	v_xor_b32_e32 v34, v34, v49
	v_lshl_add_u32 v34, v34, 1, v47
	ds_read_b128 v[34:37], v34 offset:8960
	s_waitcnt lgkmcnt(0)
	v_mfma_f32_16x16x32_bf16 v[30:33], v[10:13], v[34:37], v[30:33]
	v_cndmask_b32_e64 v34, 0, v43, s[40:41]
	v_xor_b32_e32 v34, v34, v50
	v_lshl_add_u32 v34, v34, 1, v47
	ds_read_b128 v[34:37], v34 offset:8960
	s_waitcnt lgkmcnt(0)
	v_mfma_f32_16x16x32_bf16 v[30:33], v[6:9], v[34:37], v[30:33]
	v_cndmask_b32_e64 v34, 0, v43, s[42:43]
	v_xor_b32_e32 v34, v34, v52
	v_lshl_add_u32 v34, v34, 1, v47
	ds_read_b128 v[34:37], v34 offset:8960
	v_or_b32_e32 v43, 32, v46
	s_waitcnt lgkmcnt(0)
	v_mfma_f32_16x16x32_bf16 v[30:33], v[2:5], v[34:37], v[30:33]
	s_nop 7
	v_mul_f32_e32 v30, v39, v30
	v_bfe_u32 v34, v30, 16, 1
	v_add3_u32 v30, v30, v34, s72
	ds_write_b16_d16_hi v53, v30 offset:32
	v_mul_f32_e32 v30, v41, v31
	v_bfe_u32 v31, v30, 16, 1
	v_add3_u32 v30, v30, v31, s72
	ds_write_b16_d16_hi v40, v30 offset:32
	v_mul_f32_e32 v30, v42, v32
	v_bfe_u32 v31, v30, 16, 1
	v_add3_u32 v30, v30, v31, s72
	ds_write_b16_d16_hi v40, v30 offset:304
	v_mul_f32_e32 v30, v44, v33
	v_bfe_u32 v31, v30, 16, 1
	v_add3_u32 v30, v30, v31, s72
	ds_write_b16_d16_hi v40, v30 offset:576
	v_cndmask_b32_e32 v30, 0, v43, vcc
	v_xor_b32_e32 v30, v30, v45
	v_lshl_add_u32 v30, v30, 1, v47
	ds_read_b128 v[30:33], v30 offset:17920
	v_cndmask_b32_e64 v34, 0, v43, s[0:1]
	v_xor_b32_e32 v34, v34, v48
	v_lshl_add_u32 v34, v34, 1, v47
	ds_read_b128 v[34:37], v34 offset:17920
	s_waitcnt lgkmcnt(1)
	v_mfma_f32_16x16x32_bf16 v[30:33], v[18:21], v[30:33], 0
	s_waitcnt lgkmcnt(0)
	v_mfma_f32_16x16x32_bf16 v[30:33], v[14:17], v[34:37], v[30:33]
	v_cndmask_b32_e64 v34, 0, v43, s[38:39]
	v_xor_b32_e32 v34, v34, v49
	v_lshl_add_u32 v34, v34, 1, v47
	ds_read_b128 v[34:37], v34 offset:17920
	s_waitcnt lgkmcnt(0)
	v_mfma_f32_16x16x32_bf16 v[30:33], v[10:13], v[34:37], v[30:33]
	v_cndmask_b32_e64 v34, 0, v43, s[40:41]
	v_xor_b32_e32 v34, v34, v50
	v_lshl_add_u32 v34, v34, 1, v47
	ds_read_b128 v[34:37], v34 offset:17920
	s_waitcnt lgkmcnt(0)
	v_mfma_f32_16x16x32_bf16 v[30:33], v[6:9], v[34:37], v[30:33]
	v_cndmask_b32_e64 v34, 0, v43, s[42:43]
	v_xor_b32_e32 v34, v34, v52
	v_lshl_add_u32 v34, v34, 1, v47
	ds_read_b128 v[34:37], v34 offset:17920
	v_or_b32_e32 v43, 48, v46
	s_waitcnt lgkmcnt(0)
	v_mfma_f32_16x16x32_bf16 v[30:33], v[2:5], v[34:37], v[30:33]
	s_nop 7
	v_mul_f32_e32 v30, v39, v30
	v_bfe_u32 v34, v30, 16, 1
	v_add3_u32 v30, v30, v34, s72
	ds_write_b16_d16_hi v53, v30 offset:64
	v_mul_f32_e32 v30, v41, v31
	v_bfe_u32 v31, v30, 16, 1
	v_add3_u32 v30, v30, v31, s72
	ds_write_b16_d16_hi v40, v30 offset:64
	v_mul_f32_e32 v30, v42, v32
	v_bfe_u32 v31, v30, 16, 1
	v_add3_u32 v30, v30, v31, s72
	ds_write_b16_d16_hi v40, v30 offset:336
	v_mul_f32_e32 v30, v44, v33
	v_bfe_u32 v31, v30, 16, 1
	v_add3_u32 v30, v30, v31, s72
	ds_write_b16_d16_hi v40, v30 offset:608
	v_cndmask_b32_e32 v30, 0, v43, vcc
	v_xor_b32_e32 v30, v30, v45
	v_lshl_add_u32 v30, v30, 1, v47
	ds_read_b128 v[30:33], v30 offset:26880
	v_cndmask_b32_e64 v34, 0, v43, s[0:1]
	v_xor_b32_e32 v34, v34, v48
	v_lshl_add_u32 v34, v34, 1, v47
	ds_read_b128 v[34:37], v34 offset:26880
	s_waitcnt lgkmcnt(1)
	v_mfma_f32_16x16x32_bf16 v[30:33], v[18:21], v[30:33], 0
	s_waitcnt lgkmcnt(0)
	v_mfma_f32_16x16x32_bf16 v[30:33], v[14:17], v[34:37], v[30:33]
	v_cndmask_b32_e64 v34, 0, v43, s[38:39]
	v_xor_b32_e32 v34, v34, v49
	v_lshl_add_u32 v34, v34, 1, v47
	ds_read_b128 v[34:37], v34 offset:26880
	s_waitcnt lgkmcnt(0)
	v_mfma_f32_16x16x32_bf16 v[30:33], v[10:13], v[34:37], v[30:33]
	v_cndmask_b32_e64 v34, 0, v43, s[40:41]
	v_xor_b32_e32 v34, v34, v50
	v_lshl_add_u32 v34, v34, 1, v47
	ds_read_b128 v[34:37], v34 offset:26880
	s_waitcnt lgkmcnt(0)
	v_mfma_f32_16x16x32_bf16 v[30:33], v[6:9], v[34:37], v[30:33]
	v_cndmask_b32_e64 v34, 0, v43, s[42:43]
	v_xor_b32_e32 v34, v34, v52
	v_lshl_add_u32 v34, v34, 1, v47
	ds_read_b128 v[34:37], v34 offset:26880
	v_or_b32_e32 v43, 64, v46
	s_waitcnt lgkmcnt(0)
; __device__ void swa_item(const Params& p, int item) {
;     ...
;   _Pragma("unroll") for (int dt = 0; dt < 8; ++dt) {
;     f32x4 a = (f32x4){0.f, 0.f, 0.f, 0.f};
;     _Pragma("unroll") for (int kk = 0; kk < 5; ++kk) {
;       const int k0_ = w * 16 + kk * 32 + q * 8; const int ch_ = k0_ >> 3;
;       const int chp_ = (ch_ < 32) ? (ch_ ^ (((dt * 16 + c) >> 3) & 15)) : ch_;
;       bf16x8 vf = *(const bf16x8*)(Vt + (dt * 16 + c) * 280 + chp_ * 8);
;       a = __builtin_amdgcn_mfma_f32_16x16x32_bf16(pf[kk], vf, a, 0, 0, 0);
;     }
;     _Pragma("unroll") for (int jj = 0; jj < 4; ++jj) Ow[(q * 4 + jj) * 136 + dt * 16 + c] = f2bf(a[jj] * il[jj]);
	v_mfma_f32_16x16x32_bf16 v[30:33], v[2:5], v[34:37], v[30:33]
	s_nop 7
	v_mul_f32_e32 v30, v39, v30
	v_bfe_u32 v34, v30, 16, 1
	v_add3_u32 v30, v30, v34, s72
	ds_write_b16_d16_hi v53, v30 offset:96
	v_mul_f32_e32 v30, v41, v31
	v_bfe_u32 v31, v30, 16, 1
	v_add3_u32 v30, v30, v31, s72
	ds_write_b16_d16_hi v40, v30 offset:96
	v_mul_f32_e32 v30, v42, v32
	v_bfe_u32 v31, v30, 16, 1
	v_add3_u32 v30, v30, v31, s72
	ds_write_b16_d16_hi v40, v30 offset:368
	v_mul_f32_e32 v30, v44, v33
	v_bfe_u32 v31, v30, 16, 1
	v_add3_u32 v30, v30, v31, s72
	ds_write_b16_d16_hi v40, v30 offset:640
	v_cndmask_b32_e32 v30, 0, v43, vcc
	v_xor_b32_e32 v30, v30, v45
	v_lshl_add_u32 v30, v30, 1, v47
	ds_read_b128 v[30:33], v30 offset:35840
	v_cndmask_b32_e64 v34, 0, v43, s[0:1]
	v_xor_b32_e32 v34, v34, v48
	v_lshl_add_u32 v34, v34, 1, v47
	ds_read_b128 v[34:37], v34 offset:35840
	s_waitcnt lgkmcnt(1)
	v_mfma_f32_16x16x32_bf16 v[30:33], v[18:21], v[30:33], 0
	s_waitcnt lgkmcnt(0)
	v_mfma_f32_16x16x32_bf16 v[30:33], v[14:17], v[34:37], v[30:33]
	v_cndmask_b32_e64 v34, 0, v43, s[38:39]
	v_xor_b32_e32 v34, v34, v49
	v_lshl_add_u32 v34, v34, 1, v47
	ds_read_b128 v[34:37], v34 offset:35840
	s_waitcnt lgkmcnt(0)
	v_mfma_f32_16x16x32_bf16 v[30:33], v[10:13], v[34:37], v[30:33]
	v_cndmask_b32_e64 v34, 0, v43, s[40:41]
	v_xor_b32_e32 v34, v34, v50
	v_lshl_add_u32 v34, v34, 1, v47
	ds_read_b128 v[34:37], v34 offset:35840
	s_waitcnt lgkmcnt(0)
	v_mfma_f32_16x16x32_bf16 v[30:33], v[6:9], v[34:37], v[30:33]
	v_cndmask_b32_e64 v34, 0, v43, s[42:43]
	v_xor_b32_e32 v34, v34, v52
	v_lshl_add_u32 v34, v34, 1, v47
	ds_read_b128 v[34:37], v34 offset:35840
	v_or_b32_e32 v43, 0x50, v46
	s_waitcnt lgkmcnt(0)
	v_mfma_f32_16x16x32_bf16 v[30:33], v[2:5], v[34:37], v[30:33]
	s_nop 7
	v_mul_f32_e32 v30, v39, v30
	v_bfe_u32 v34, v30, 16, 1
	v_add3_u32 v30, v30, v34, s72
	ds_write_b16_d16_hi v53, v30 offset:128
	v_mul_f32_e32 v30, v41, v31
	v_bfe_u32 v31, v30, 16, 1
	v_add3_u32 v30, v30, v31, s72
	ds_write_b16_d16_hi v40, v30 offset:128
	v_mul_f32_e32 v30, v42, v32
	v_bfe_u32 v31, v30, 16, 1
	v_add3_u32 v30, v30, v31, s72
	ds_write_b16_d16_hi v40, v30 offset:400
	v_mul_f32_e32 v30, v44, v33
	v_bfe_u32 v31, v30, 16, 1
	v_add3_u32 v30, v30, v31, s72
	ds_write_b16_d16_hi v40, v30 offset:672
	v_cndmask_b32_e32 v30, 0, v43, vcc
	v_xor_b32_e32 v30, v30, v45
	v_lshl_add_u32 v30, v30, 1, v47
	ds_read_b128 v[30:33], v30 offset:44800
	v_cndmask_b32_e64 v34, 0, v43, s[0:1]
	v_xor_b32_e32 v34, v34, v48
	v_lshl_add_u32 v34, v34, 1, v47
	ds_read_b128 v[34:37], v34 offset:44800
	s_waitcnt lgkmcnt(1)
	v_mfma_f32_16x16x32_bf16 v[30:33], v[18:21], v[30:33], 0
	s_waitcnt lgkmcnt(0)
	v_mfma_f32_16x16x32_bf16 v[30:33], v[14:17], v[34:37], v[30:33]
	v_cndmask_b32_e64 v34, 0, v43, s[38:39]
	v_xor_b32_e32 v34, v34, v49
	v_lshl_add_u32 v34, v34, 1, v47
	ds_read_b128 v[34:37], v34 offset:44800
	s_waitcnt lgkmcnt(0)
	v_mfma_f32_16x16x32_bf16 v[30:33], v[10:13], v[34:37], v[30:33]
	v_cndmask_b32_e64 v34, 0, v43, s[40:41]
	v_xor_b32_e32 v34, v34, v50
	v_lshl_add_u32 v34, v34, 1, v47
	ds_read_b128 v[34:37], v34 offset:44800
	s_waitcnt lgkmcnt(0)
	v_mfma_f32_16x16x32_bf16 v[30:33], v[6:9], v[34:37], v[30:33]
	v_cndmask_b32_e64 v34, 0, v43, s[42:43]
	v_xor_b32_e32 v34, v34, v52
	v_lshl_add_u32 v34, v34, 1, v47
	ds_read_b128 v[34:37], v34 offset:44800
	v_or_b32_e32 v43, 0x60, v46
	s_waitcnt lgkmcnt(0)
	v_mfma_f32_16x16x32_bf16 v[30:33], v[2:5], v[34:37], v[30:33]
	s_nop 7
	v_mul_f32_e32 v30, v39, v30
	v_bfe_u32 v34, v30, 16, 1
	v_add3_u32 v30, v30, v34, s72
	ds_write_b16_d16_hi v53, v30 offset:160
	v_mul_f32_e32 v30, v41, v31
	v_bfe_u32 v31, v30, 16, 1
	v_add3_u32 v30, v30, v31, s72
	ds_write_b16_d16_hi v40, v30 offset:160
	v_mul_f32_e32 v30, v42, v32
	v_bfe_u32 v31, v30, 16, 1
	v_add3_u32 v30, v30, v31, s72
	ds_write_b16_d16_hi v40, v30 offset:432
	v_mul_f32_e32 v30, v44, v33
	v_bfe_u32 v31, v30, 16, 1
	v_add3_u32 v30, v30, v31, s72
	ds_write_b16_d16_hi v40, v30 offset:704
	v_cndmask_b32_e32 v30, 0, v43, vcc
	v_xor_b32_e32 v30, v30, v45
	v_lshl_add_u32 v30, v30, 1, v47
	ds_read_b128 v[30:33], v30 offset:53760
	v_cndmask_b32_e64 v34, 0, v43, s[0:1]
	v_xor_b32_e32 v34, v34, v48
	v_lshl_add_u32 v34, v34, 1, v47
	ds_read_b128 v[34:37], v34 offset:53760
	s_waitcnt lgkmcnt(1)
	v_mfma_f32_16x16x32_bf16 v[30:33], v[18:21], v[30:33], 0
	s_waitcnt lgkmcnt(0)
	v_mfma_f32_16x16x32_bf16 v[30:33], v[14:17], v[34:37], v[30:33]
	v_cndmask_b32_e64 v34, 0, v43, s[38:39]
	v_xor_b32_e32 v34, v34, v49
	v_lshl_add_u32 v34, v34, 1, v47
	ds_read_b128 v[34:37], v34 offset:53760
	s_waitcnt lgkmcnt(0)
	v_mfma_f32_16x16x32_bf16 v[30:33], v[10:13], v[34:37], v[30:33]
	v_cndmask_b32_e64 v34, 0, v43, s[40:41]
	v_xor_b32_e32 v34, v34, v50
	v_lshl_add_u32 v34, v34, 1, v47
	ds_read_b128 v[34:37], v34 offset:53760
	s_waitcnt lgkmcnt(0)
	v_mfma_f32_16x16x32_bf16 v[30:33], v[6:9], v[34:37], v[30:33]
	v_cndmask_b32_e64 v34, 0, v43, s[42:43]
	v_xor_b32_e32 v34, v34, v52
	v_lshl_add_u32 v34, v34, 1, v47
	ds_read_b128 v[34:37], v34 offset:53760
	s_waitcnt lgkmcnt(0)
; __device__ __forceinline__ float flog(float x) { return __builtin_amdgcn_logf(x) * 0.6931471805599453f; }
; __device__ void swa_item(const Params& p, int item) {
;     ...
;   _Pragma("unroll") for (int dt = 0; dt < 8; ++dt) {
;     f32x4 a = (f32x4){0.f, 0.f, 0.f, 0.f};
;     _Pragma("unroll") for (int kk = 0; kk < 5; ++kk) {
;       const int k0_ = w * 16 + kk * 32 + q * 8; const int ch_ = k0_ >> 3;
;       const int chp_ = (ch_ < 32) ? (ch_ ^ (((dt * 16 + c) >> 3) & 15)) : ch_;
;       bf16x8 vf = *(const bf16x8*)(Vt + (dt * 16 + c) * 280 + chp_ * 8);
;       a = __builtin_amdgcn_mfma_f32_16x16x32_bf16(pf[kk], vf, a, 0, 0, 0);
;     }
;     _Pragma("unroll") for (int jj = 0; jj < 4; ++jj) Ow[(q * 4 + jj) * 136 + dt * 16 + c] = f2bf(a[jj] * il[jj]);
;   }
;   asm volatile("s_waitcnt lgkmcnt(0)" ::: "memory");
;   _Pragma("unroll") for (int i = 0; i < 4; ++i) {
;     const int id = lane + 64 * i; const int rr = id >> 4, c8 = id & 15;
;     long orow = rowb + (long)(qb * 128 + w * 16 + rr) * dil + r;
;     *(bf16x8*)(buf + orow * 4608 + qcol + c8 * 8) = *(const bf16x8*)(Ow + rr * 136 + c8 * 8);
;   }
;   if (c == 0) {
;     _Pragma("unroll") for (int jj = 0; jj < 4; ++jj) {
;       long orow = rowb + (long)(qb * 128 + w * 16 + q * 4 + jj) * dil + r;
;       misc[MF_LSE + ((long)pat * MTOK + orow) * 4 + head] = mx[jj] + flog(ls[jj]);
;     }
;   }
	v_mfma_f32_16x16x32_bf16 v[30:33], v[2:5], v[34:37], v[30:33]
	s_nop 7
	v_mul_f32_e32 v30, v39, v30
	v_bfe_u32 v34, v30, 16, 1
	v_add3_u32 v30, v30, v34, s72
	ds_write_b16_d16_hi v53, v30 offset:192
	v_mul_f32_e32 v30, v41, v31
	v_bfe_u32 v31, v30, 16, 1
	v_add3_u32 v30, v30, v31, s72
	ds_write_b16_d16_hi v40, v30 offset:192
	v_mul_f32_e32 v30, v42, v32
	v_bfe_u32 v31, v30, 16, 1
	v_add3_u32 v30, v30, v31, s72
	ds_write_b16_d16_hi v40, v30 offset:464
	v_mul_f32_e32 v30, v44, v33
	v_bfe_u32 v31, v30, 16, 1
	v_add3_u32 v30, v30, v31, s72
	v_or_b32_e32 v34, 0x70, v46
	ds_write_b16_d16_hi v40, v30 offset:736
	v_cndmask_b32_e32 v30, 0, v34, vcc
	v_xor_b32_e32 v30, v30, v45
	v_lshl_add_u32 v30, v30, 1, v47
	ds_read_b128 v[30:33], v30 offset:62720
	v_cmp_eq_u32_e32 vcc, 0, v55
	s_waitcnt lgkmcnt(0)
	v_mfma_f32_16x16x32_bf16 v[18:21], v[18:21], v[30:33], 0
	v_cndmask_b32_e64 v30, 0, v34, s[0:1]
	v_xor_b32_e32 v30, v30, v48
	v_lshl_add_u32 v30, v30, 1, v47
	ds_read_b128 v[30:33], v30 offset:62720
	s_waitcnt lgkmcnt(0)
	v_mfma_f32_16x16x32_bf16 v[14:17], v[14:17], v[30:33], v[18:21]
	s_nop 2
	v_cndmask_b32_e64 v18, 0, v34, s[38:39]
	v_xor_b32_e32 v18, v18, v49
	v_lshl_add_u32 v18, v18, 1, v47
	ds_read_b128 v[18:21], v18 offset:62720
	s_waitcnt lgkmcnt(0)
	v_mfma_f32_16x16x32_bf16 v[10:13], v[10:13], v[18:21], v[14:17]
	s_nop 2
	v_cndmask_b32_e64 v14, 0, v34, s[40:41]
	v_xor_b32_e32 v14, v14, v50
	v_lshl_add_u32 v14, v14, 1, v47
	ds_read_b128 v[14:17], v14 offset:62720
	s_waitcnt lgkmcnt(0)
	v_mfma_f32_16x16x32_bf16 v[6:9], v[6:9], v[14:17], v[10:13]
	s_nop 2
	v_cndmask_b32_e64 v10, 0, v34, s[42:43]
	v_xor_b32_e32 v10, v10, v52
	v_lshl_add_u32 v10, v10, 1, v47
	ds_read_b128 v[10:13], v10 offset:62720
	s_waitcnt lgkmcnt(0)
	v_mfma_f32_16x16x32_bf16 v[2:5], v[2:5], v[10:13], v[6:9]
	s_nop 2
	v_or_b32_e32 v8, v51, v56
	v_ashrrev_i32_e32 v9, 31, v8
	s_nop 2
	v_mul_f32_e32 v2, v39, v2
	v_bfe_u32 v6, v2, 16, 1
	v_add3_u32 v2, v2, v6, s72
	ds_write_b16_d16_hi v53, v2 offset:224
	v_mul_f32_e32 v2, v41, v3
	v_bfe_u32 v3, v2, 16, 1
	v_add3_u32 v2, v2, v3, s72
	ds_write_b16_d16_hi v40, v2 offset:224
	v_mul_f32_e32 v2, v42, v4
	v_bfe_u32 v3, v2, 16, 1
	v_add3_u32 v2, v2, v3, s72
	ds_write_b16_d16_hi v40, v2 offset:496
	v_mul_f32_e32 v2, v44, v5
	v_bfe_u32 v3, v2, 16, 1
	v_add3_u32 v2, v2, v3, s72
	ds_write_b16_d16_hi v40, v2 offset:768
	v_lshlrev_b64 v[2:3], s22, v[8:9]
	v_lshl_add_u64 v[10:11], v[2:3], 0, s[26:27]
	v_mul_u32_u24_e32 v2, 0x110, v56
	s_waitcnt lgkmcnt(0)
	v_lshl_add_u64 v[6:7], s[52:53], 0, v[0:1]
	v_add3_u32 v0, v57, v0, v2
	ds_read_b128 v[2:5], v0
	v_mad_u64_u32 v[12:13], s[0:1], v10, s89, v[6:7]
	v_mad_i32_i24 v13, v11, s89, v13
	s_waitcnt lgkmcnt(0)
	global_store_dwordx4 v[12:13], v[2:5], off
	s_nop 1
	v_or_b32_e32 v2, 4, v8
	v_ashrrev_i32_e32 v3, 31, v2
	v_lshlrev_b64 v[2:3], s22, v[2:3]
	v_lshl_add_u64 v[10:11], v[2:3], 0, s[26:27]
	ds_read_b128 v[2:5], v0 offset:1088
	v_mad_u64_u32 v[12:13], s[0:1], v10, s89, v[6:7]
	v_mad_i32_i24 v13, v11, s89, v13
	s_waitcnt lgkmcnt(0)
	global_store_dwordx4 v[12:13], v[2:5], off
	s_nop 1
	v_or_b32_e32 v2, 8, v8
	v_ashrrev_i32_e32 v3, 31, v2
	v_lshlrev_b64 v[2:3], s22, v[2:3]
	v_lshl_add_u64 v[10:11], v[2:3], 0, s[26:27]
	ds_read_b128 v[2:5], v0 offset:2176
	v_mad_u64_u32 v[12:13], s[0:1], v10, s89, v[6:7]
	v_mad_i32_i24 v13, v11, s89, v13
	s_waitcnt lgkmcnt(0)
	global_store_dwordx4 v[12:13], v[2:5], off
	s_nop 1
	v_or_b32_e32 v2, 12, v8
	v_ashrrev_i32_e32 v3, 31, v2
	v_lshlrev_b64 v[2:3], s22, v[2:3]
	v_lshl_add_u64 v[8:9], v[2:3], 0, s[26:27]
	ds_read_b128 v[2:5], v0 offset:3264
	v_mad_u64_u32 v[6:7], s[0:1], v8, s89, v[6:7]
	v_mad_i32_i24 v7, v9, s89, v7
	s_waitcnt lgkmcnt(0)
	global_store_dwordx4 v[6:7], v[2:5], off
	s_and_saveexec_b64 s[0:1], vcc
	s_cbranch_execz .LBB0_101
	s_ashr_i32 s89, s88, 31
	s_lshl_b64 s[2:3], s[88:89], 19
	v_readlane_b32 s12, v252, 20
	v_log_f32_e32 v0, v26
	s_add_u32 s2, s12, s2
	v_readlane_b32 s12, v252, 21
	v_or_b32_e32 v2, v51, v38
	s_addc_u32 s3, s12, s3
	s_lshl_b32 s12, s23, 2
	s_add_u32 s2, s2, s12
	v_ashrrev_i32_e32 v3, 31, v2
	v_readlane_b32 s12, v254, 13
	v_lshlrev_b64 v[4:5], s22, v[2:3]
	v_readlane_b32 s13, v254, 14
	v_fmac_f32_e32 v22, 0x3f317218, v0
	v_log_f32_e32 v0, v27
	s_addc_u32 s3, s3, 0
	v_lshl_add_u64 v[4:5], v[4:5], 0, s[12:13]
	v_lshl_add_u64 v[4:5], v[4:5], 4, s[2:3]
	global_store_dword v[4:5], v22, off
	v_or_b32_e32 v4, 1, v2
	v_ashrrev_i32_e32 v5, 31, v4
	v_fmac_f32_e32 v23, 0x3f317218, v0
	v_log_f32_e32 v0, v28
	v_lshlrev_b64 v[4:5], s22, v[4:5]
	v_lshl_add_u64 v[4:5], v[4:5], 0, s[12:13]
	v_lshl_add_u64 v[4:5], v[4:5], 4, s[2:3]
	global_store_dword v[4:5], v23, off
	v_or_b32_e32 v4, 2, v2
	v_fmac_f32_e32 v24, 0x3f317218, v0
	v_or_b32_e32 v2, 3, v2
	v_log_f32_e32 v0, v29
	v_ashrrev_i32_e32 v5, 31, v4
	v_ashrrev_i32_e32 v3, 31, v2
	v_lshlrev_b64 v[4:5], s22, v[4:5]
	v_lshlrev_b64 v[2:3], s22, v[2:3]
	v_lshl_add_u64 v[4:5], v[4:5], 0, s[12:13]
	v_lshl_add_u64 v[2:3], v[2:3], 0, s[12:13]
	s_movk_i32 s89, 0x2400
	v_lshl_add_u64 v[4:5], v[4:5], 4, s[2:3]
	v_fmac_f32_e32 v25, 0x3f317218, v0
	v_lshl_add_u64 v[2:3], v[2:3], 4, s[2:3]
	global_store_dword v[4:5], v24, off
	global_store_dword v[2:3], v25, off
	s_branch .LBB0_101
